# ffn_up epilogue: RMSNorm row-factor partial loads issued in two batches of four rows instead of serially
# speedup vs baseline: 1.0083x; 1.0020x over previous
; __device__ __forceinline__ float rs_from_partials(const float* SSP, int row, int fq) {
;     const f32x4 a = *(const f32x4*)(SSP + (size_t)row * 32 + 8 * fq), b = *(const f32x4*)(SSP + (size_t)row * 32 + 8 * fq + 4);
;     float s = ((a[0] + a[1]) + (a[2] + a[3])) + ((b[0] + b[1]) + (b[2] + b[3]));
;     s += __shfl_xor(s, 16); s += __shfl_xor(s, 32);
;     return __builtin_amdgcn_rsqf(s * (1.f / 2048.f) + 1e-6f);
; }
;     __device__ __forceinline__ void operator()(const f32x4 (&acc)[2][2][4][2], const Unit& u, int wr, int wc, int fr, int fq) const {
;         const int row0 = u.pm * BM + wr * 64 + fr, cidx = wc * 32 + 8 * fq;
;         float rs[2][4];
; #pragma unroll
;         for (int ai = 0; ai < 2; ++ai)
; #pragma unroll
;             for (int m = 0; m < 4; ++m) rs[ai][m] = rs_from_partials(SS, row0 + ai * HALF + m * 16, fq);
.LBB0_1888:
	v_and_b32_e32 v130, 64, v254
	v_xor_b32_e32 v128, 16, v254
	v_add_u32_e32 v130, 64, v130
	v_cmp_lt_i32_e32 vcc, v128, v130
	v_lshl_add_u32 v228, s10, 8, v181
	v_ashrrev_i32_e32 v229, 31, v228
	v_cndmask_b32_e32 v128, v254, v128, vcc
	v_lshlrev_b32_e32 v138, 2, v128
	v_xor_b32_e32 v128, 32, v254
	v_cmp_lt_i32_e32 vcc, v128, v130
	v_or_b32_e32 v226, 16, v228
	v_ashrrev_i32_e32 v227, 31, v226
	v_or_b32_e32 v224, 32, v228
	v_ashrrev_i32_e32 v225, 31, v224
	v_or_b32_e32 v220, 48, v228
	v_ashrrev_i32_e32 v221, 31, v220
	v_cndmask_b32_e32 v128, v254, v128, vcc
	v_lshlrev_b32_e32 v128, 2, v128
	v_add_u32_e32 v216, 0x80, v228
	v_ashrrev_i32_e32 v217, 31, v216
	v_add_u32_e32 v212, 0x90, v228
	v_ashrrev_i32_e32 v213, 31, v212
	v_add_u32_e32 v208, 0xa0, v228
	v_ashrrev_i32_e32 v209, 31, v208
	v_add_u32_e32 v200, 0xb0, v228
	v_ashrrev_i32_e32 v201, 31, v200
	s_ashr_i32 s11, s10, 31
	s_lshl_b64 s[48:49], s[10:11], 2
	v_lshlrev_b64 v[140:141], 7, v[228:229]
	v_lshl_add_u64 v[140:141], v[188:189], 0, v[140:141]
	global_load_dwordx4 v[130:133], v[140:141], off offset:16
	global_load_dwordx4 v[134:137], v[140:141], off
	v_lshlrev_b64 v[140:141], 7, v[226:227]
	v_lshl_add_u64 v[140:141], v[188:189], 0, v[140:141]
	global_load_dwordx4 v[148:151], v[140:141], off offset:16
	global_load_dwordx4 v[152:155], v[140:141], off
	v_lshlrev_b64 v[140:141], 7, v[224:225]
	v_lshl_add_u64 v[140:141], v[188:189], 0, v[140:141]
	global_load_dwordx4 v[156:159], v[140:141], off offset:16
	global_load_dwordx4 v[160:163], v[140:141], off
	v_lshlrev_b64 v[140:141], 7, v[220:221]
	v_lshl_add_u64 v[140:141], v[188:189], 0, v[140:141]
	global_load_dwordx4 v[164:167], v[140:141], off offset:16
	global_load_dwordx4 v[202:205], v[140:141], off
	s_waitcnt vmcnt(6)
	v_add_f32_e32 v130, v130, v131
	v_add_f32_e32 v134, v134, v135
	v_add_f32_e32 v135, v136, v137
	v_add_f32_e32 v131, v132, v133
	v_add_f32_e32 v134, v134, v135
	v_add_f32_e32 v130, v130, v131
	v_add_f32_e32 v142, v134, v130
	s_waitcnt vmcnt(4)
	v_add_f32_e32 v148, v148, v149
	v_add_f32_e32 v152, v152, v153
	v_add_f32_e32 v153, v154, v155
	v_add_f32_e32 v149, v150, v151
	v_add_f32_e32 v152, v152, v153
	v_add_f32_e32 v148, v148, v149
	v_add_f32_e32 v214, v152, v148
	s_waitcnt vmcnt(2)
	v_add_f32_e32 v156, v156, v157
	v_add_f32_e32 v160, v160, v161
	v_add_f32_e32 v161, v162, v163
	v_add_f32_e32 v157, v158, v159
	v_add_f32_e32 v160, v160, v161
	v_add_f32_e32 v156, v156, v157
	v_add_f32_e32 v219, v160, v156
	s_waitcnt vmcnt(0)
	v_add_f32_e32 v164, v164, v165
	v_add_f32_e32 v202, v202, v203
	v_add_f32_e32 v203, v204, v205
	v_add_f32_e32 v165, v166, v167
	v_add_f32_e32 v202, v202, v203
	v_add_f32_e32 v164, v164, v165
	v_add_f32_e32 v210, v202, v164
	v_lshlrev_b64 v[140:141], 7, v[216:217]
	v_lshl_add_u64 v[140:141], v[188:189], 0, v[140:141]
	global_load_dwordx4 v[130:133], v[140:141], off offset:16
	global_load_dwordx4 v[134:137], v[140:141], off
	v_lshlrev_b64 v[140:141], 7, v[212:213]
	v_lshl_add_u64 v[140:141], v[188:189], 0, v[140:141]
	global_load_dwordx4 v[148:151], v[140:141], off offset:16
	global_load_dwordx4 v[152:155], v[140:141], off
	v_lshlrev_b64 v[140:141], 7, v[208:209]
	v_lshl_add_u64 v[140:141], v[188:189], 0, v[140:141]
	global_load_dwordx4 v[156:159], v[140:141], off offset:16
	global_load_dwordx4 v[160:163], v[140:141], off
	v_lshlrev_b64 v[140:141], 7, v[200:201]
	v_lshl_add_u64 v[140:141], v[188:189], 0, v[140:141]
	global_load_dwordx4 v[164:167], v[140:141], off offset:16
	global_load_dwordx4 v[202:205], v[140:141], off
	ds_bpermute_b32 v222, v138, v142
	ds_bpermute_b32 v223, v138, v214
	ds_bpermute_b32 v218, v138, v219
	ds_bpermute_b32 v168, v138, v210
	s_waitcnt lgkmcnt(3)
	v_add_f32_e32 v142, v142, v222
	s_waitcnt lgkmcnt(2)
	v_add_f32_e32 v214, v214, v223
	s_waitcnt lgkmcnt(1)
	v_add_f32_e32 v219, v219, v218
	s_waitcnt lgkmcnt(0)
	v_add_f32_e32 v210, v210, v168
	ds_bpermute_b32 v143, v128, v142
	ds_bpermute_b32 v215, v128, v214
	ds_bpermute_b32 v225, v128, v219
	ds_bpermute_b32 v169, v128, v210
	s_waitcnt vmcnt(6)
	v_add_f32_e32 v130, v130, v131
	v_add_f32_e32 v134, v134, v135
	v_add_f32_e32 v135, v136, v137
	v_add_f32_e32 v131, v132, v133
	v_add_f32_e32 v134, v134, v135
	v_add_f32_e32 v130, v130, v131
	v_add_f32_e32 v144, v134, v130
	s_waitcnt vmcnt(4)
	v_add_f32_e32 v148, v148, v149
	v_add_f32_e32 v152, v152, v153
	v_add_f32_e32 v153, v154, v155
	v_add_f32_e32 v149, v150, v151
	v_add_f32_e32 v152, v152, v153
	v_add_f32_e32 v148, v148, v149
	v_add_f32_e32 v199, v152, v148
	s_waitcnt vmcnt(2)
	v_add_f32_e32 v156, v156, v157
	v_add_f32_e32 v160, v160, v161
	v_add_f32_e32 v161, v162, v163
	v_add_f32_e32 v157, v158, v159
	v_add_f32_e32 v160, v160, v161
	v_add_f32_e32 v156, v156, v157
	v_add_f32_e32 v209, v160, v156
	s_waitcnt vmcnt(0)
	v_add_f32_e32 v164, v164, v165
	v_add_f32_e32 v202, v202, v203
	v_add_f32_e32 v203, v204, v205
	v_add_f32_e32 v165, v166, v167
	v_add_f32_e32 v202, v202, v203
	v_add_f32_e32 v164, v164, v165
	v_add_f32_e32 v146, v202, v164
	s_waitcnt lgkmcnt(0)
	v_add_f32_e32 v210, v210, v169
	v_fmamk_f32 v210, v210, 0x3a000000, v241
	v_rsq_f32_e32 v194, v210
	ds_bpermute_b32 v222, v138, v144
	ds_bpermute_b32 v223, v138, v199
	ds_bpermute_b32 v218, v138, v209
	ds_bpermute_b32 v168, v138, v146
	s_waitcnt lgkmcnt(3)
	v_add_f32_e32 v144, v144, v222
	s_waitcnt lgkmcnt(2)
	v_add_f32_e32 v199, v199, v223
	s_waitcnt lgkmcnt(1)
	v_add_f32_e32 v209, v209, v218
	s_waitcnt lgkmcnt(0)
	v_add_f32_e32 v146, v146, v168
	ds_bpermute_b32 v145, v128, v144
	ds_bpermute_b32 v211, v128, v199
	ds_bpermute_b32 v213, v128, v209
	ds_bpermute_b32 v147, v128, v146
	s_waitcnt lgkmcnt(1)
	v_lshl_add_u64 v[130:131], v[182:183], 0, s[48:49]
	v_mad_u64_u32 v[138:139], s[10:11], v130, s54, 0
	s_lshl_b32 s10, s8, 7
	v_mad_i32_i24 v139, v131, s54, v139
	s_ashr_i32 s11, s10, 31
	s_and_saveexec_b64 s[8:9], s[4:5]
	s_movk_i32 s38, 0xfec0
	s_cbranch_execz .LBB0_1897
	v_mov_b32_e32 v140, v194
	v_mov_b32_e32 v141, v194
	v_pk_mul_f32 v[136:137], v[102:103], v[194:195] op_sel_hi:[1,0]
	v_pk_mul_f32 v[134:135], v[100:101], v[194:195] op_sel_hi:[1,0]
	s_mov_b64 s[74:75], -1
	s_and_b64 vcc, exec, s[20:21]
	v_pk_mul_f32 v[130:131], v[36:37], v[140:141]
	ds_write_b128 v252, v[134:137]
	s_cbranch_vccz .LBB0_1891
	v_mov_b32_e32 v195, v194
	v_pk_mul_f32 v[132:133], v[38:39], v[194:195]
	s_mov_b64 s[74:75], 0
